# P2: half of the workgroups (blockIdx bit 3) run attention before pooling so the HBM-bound pooling overlaps the compute-bound attention chip-wide
# speedup vs baseline: 1.0059x; 1.0059x over previous
; __host__ __device__ __forceinline__ size_t tl_off(int row, int k, int K) { return ((((size_t)(row >> 4) * (size_t)(K >> 5)) + (size_t)(k >> 5)) << 9) + (size_t)((row & 15) * 32 + (k & 31)); }
; __device__ __forceinline__ void pool_run(const bf16_t* __restrict__ Zg, bf16_t* __restrict__ MIX, int gw, int lane) {
;     const int tb = 32 * gw, b = tb >> 12, t0 = tb & (SEQ - 1);
;     const int half = 1 << (lane >> 4);
;     const bf16_t* zb = Zg + (size_t)(b * SEQ) * NA + 8 * lane;
;     bf16_t* ob = MIX + tl_off(b * SEQ, 256 + 8 * lane, KMIX);
;     const bool qodd = lane & 4; bf16_t* pa1 = ob + (qodd ? -512 + 32 : 0); u32x4 wprev = {0u, 0u, 0u, 0u};
;     float S[8];
; #pragma unroll
;     for (int e = 0; e < 8; ++e) S[e] = 0.f;
;     {   u32x4 w[16];
; #pragma unroll
;         for (int d = 0; d < 16; ++d) { int i = t0 + d - 8; i = i < 0 ? 0 : i; i = i > SEQ - 1 ? SEQ - 1 : i; w[d] = *(const u32x4*)(zb + (size_t)i * NA); }
; #pragma unroll
;         for (int d = 0; d < 16; ++d) { const int dd = d - 8, i = t0 + dd; const float mk = (dd >= -half && dd < half && i >= 0 && i < SEQ) ? 1.f : 0.f; float v[8]; up8(w[d], v);
; #pragma unroll
;             for (int e = 0; e < 8; ++e) S[e] += mk * v[e]; } }
; __device__ __forceinline__ void p2_mixer(Frame& F) {
;     const bf16_t* Qg = F.QKVZ; const bf16_t* Kg = F.QKVZ + (size_t)M * NA; const bf16_t* Vg = F.QKVZ + 2 * (size_t)M * NA; const bf16_t* Zg = F.QKVZ + 3 * (size_t)M * NA;
;     bf16_t* MIX = F.MIX;
;     for (int gw = F.vcu * NWAVES + F.wave; gw < M / 32; gw += F.G * NWAVES) pool_run(Zg, MIX, gw, F.lane);
;     p2_attention(F, Qg, Kg, Vg, MIX);
;     __syncthreads();
; }
.LBB0_257:
	s_add_u32 s24, s28, 0x1a000000
	s_addc_u32 s25, s29, 0
	s_cmp_lt_i32 s30, 3
	s_cselect_b64 s[0:1], -1, 0
	s_cmp_gt_i32 s31, 2
	s_cselect_b64 s[4:5], -1, 0
	s_and_b64 s[0:1], s[0:1], s[4:5]
	s_andn2_b64 vcc, exec, s[0:1]
	s_cbranch_vccnz .LBB0_390
	s_bfe_u32 s98, s2, 0x10003
.Lp2_setup:
	s_waitcnt vmcnt(30)
	v_mbcnt_hi_u32_b32 v168, -1, v167
	s_lshl_b32 s44, s86, 3
	v_mov_b32_e32 v166, v168
	s_add_i32 s45, s44, s85
	s_mov_b32 s41, 0
	s_cmpk_gt_i32 s45, 0x7ff
	v_ashrrev_i32_e32 v169, 4, v166
	s_waitcnt vmcnt(1)
	v_lshlrev_b32_e32 v96, 3, v166
	s_cbranch_scc1 .LBB0_263
	s_cmp_lg_u32 s98, 1
	s_cbranch_scc1 .Lp2_pool
	s_mov_b32 s99, s86
	s_branch .LBB0_263
.Lp2_pool:
	v_ashrrev_i32_e32 v97, 31, v96
	v_lshl_add_u64 v[2:3], v[96:97], 1, s[28:29]
	v_lshlrev_b32_e64 v97, v169, 1
	v_cmp_eq_u32_e32 vcc, 31, v169
	v_add_u32_e32 v0, 0x100, v96
	s_mov_b64 s[0:1], 0x16000000
	v_cndmask_b32_e64 v104, 1.0, 0, vcc
	v_cmp_lt_i32_e32 vcc, 1, v97
	v_lshlrev_b32_e32 v4, 4, v166
	v_ashrrev_i32_e32 v98, 5, v0
	v_cndmask_b32_e64 v106, 0, 1.0, vcc
	v_cmp_lt_i32_e32 vcc, 2, v97
	v_and_b32_e32 v0, 4, v166
	v_bfe_i32 v1, v166, 2, 1
	v_cndmask_b32_e64 v108, 0, 1.0, vcc
	v_cmp_lt_i32_e32 vcc, 3, v97
	v_lshl_add_u64 v[100:101], v[2:3], 0, s[0:1]
	v_and_b32_e32 v102, 48, v4
	v_cndmask_b32_e64 v110, 0, 1.0, vcc
	v_cmp_lt_i32_e32 vcc, 4, v97
	v_mov_b32_e32 v103, 0
	s_lshl_b32 s0, s86, 8
	v_cndmask_b32_e64 v112, 0, 1.0, vcc
	v_cmp_lt_i32_e32 vcc, 5, v97
	s_lshl_b32 s1, s85, 5
	v_cmp_eq_u32_e64 s[20:21], 0, v0
	v_cndmask_b32_e64 v114, 0, 1.0, vcc
	v_cmp_lt_i32_e32 vcc, 6, v97
	v_and_b32_e32 v0, 0xfffffc40, v1
	v_lshl_add_u64 v[4:5], s[24:25], 0, v[102:103]
	v_cndmask_b32_e64 v116, 0, 1.0, vcc
	v_cmp_lt_i32_e32 vcc, 7, v97
	s_add_i32 s49, s0, s1
	s_mov_b64 s[0:1], 0x16001c00
	v_cndmask_b32_e64 v118, 0, 1.0, vcc
	s_lshl_b32 s48, s3, 3
	v_ashrrev_i32_e32 v99, 31, v98
	v_cmp_gt_i32_e64 s[4:5], 8, v97
	v_cmp_gt_i32_e64 s[6:7], 7, v97
	v_cmp_gt_i32_e64 s[8:9], 6, v97
	v_cmp_gt_i32_e64 s[10:11], 5, v97
	v_cmp_gt_i32_e64 s[12:13], 4, v97
	v_cmp_gt_i32_e64 s[14:15], 3, v97
	v_cmp_gt_i32_e64 s[16:17], 2, v97
	v_cmp_ne_u32_e64 s[18:19], 31, v169
	v_lshl_add_u64 v[120:121], v[4:5], 0, v[0:1]
	v_mov_b32_e32 v105, v104
	v_mov_b32_e32 v107, v106
	v_mov_b32_e32 v109, v108
	v_mov_b32_e32 v111, v110
	v_mov_b32_e32 v113, v112
	v_mov_b32_e32 v115, v114
	v_mov_b32_e32 v117, v116
	v_mov_b32_e32 v119, v118
	s_lshl_b32 s50, s3, 8
	v_sub_u32_e32 v170, 0, v97
	v_lshl_add_u64 v[122:123], v[2:3], 0, s[0:1]
	s_movk_i32 s51, 0xf000
	s_movk_i32 s64, 0x1000
	s_mov_b64 s[42:43], 0x2000

; #define LAS __attribute__((address_space(3)))
; #define ATT_WAIT_BAR() do { asm volatile("s_waitcnt vmcnt(0) lgkmcnt(0)" ::: "memory"); __builtin_amdgcn_s_barrier(); asm volatile("" ::: "memory"); } while (0)
; template <int KIND> __device__ __forceinline__ void attn_dma(unsigned dst, const bf16_t* src, const AttnUnit& u, int wid, int lane) {
;     const int np = u.nrows * 5;
;     const char* base = (const char*)(src + ((size_t)(u.b * NHEAD + u.h) * SEQ + u.krow_lo * 64 + 24 * u.jh) * HD);
; #pragma unroll
;     for (int it = 0; it < 10; ++it) {
;         const int pi = it * 8 + wid;
;         if (pi < np) {
;             const int w = (pi * 205) >> 10, p = pi - 5 * w, c = 8 * p + (lane >> 3);
;             const int sw = (KIND == 0) ? (((c >> 1) & 1) | (((c >> 3) & 3) << 1)) : ((((c >> 1) & 1) << 1) | (((c >> 3) & 1) << 2));
;             const int ch = (lane & 7) ^ sw;
;             const char* gp = base + (w * 64 + c) * (HD * 2) + ch * 16;
;             glds16(gp, (unsigned)__builtin_amdgcn_readfirstlane(dst + pi * 1024));
;         }
;     }
; }
; __device__ __forceinline__ void p2_attention(Frame& F, const bf16_t* Qg, const bf16_t* Kg, const bf16_t* Vg, bf16_t* MIX) {
;     const int lane = F.lane, wid = F.wave;
;     LAS unsigned char* lds = F.lds;
;     const unsigned lds0 = (unsigned)(size_t)F.lds;
;     const int q = lane & 15, g = lane >> 4;
;     constexpr int NUNITS = BATCH * NHEAD * 16, UW = 8;
;     for (int uidx = F.vcu * UW; uidx < NUNITS; uidx += F.G * UW) {
;         const int h = (uidx >> 4) & 7;
;         __syncthreads();
;         {   LAS float* tab = (LAS float*)(lds + AT_TAB);
;             for (int i = F.tid; i < 15 * 64; i += NWAVES * 64) { const int rr = i >> 6, cc = (i & 63) - 16; tab[i] = (cc >= 0 && cc < 31) ? F.rpb[h * 465 + rr * 31 + cc] * LOG2E : 0.f; } }
;         AttnUnit u = attn_decode(uidx);
;         attn_dma<0>(lds0 + AT_A, Kg, u, wid, lane);
;         bf16x8 qf[2][2];
; #pragma unroll
;         for (int jb = 0; jb < 2; ++jb) { const bf16_t* qp = Qg + ((size_t)(u.b * NHEAD + u.h) * SEQ + (u.r0 + wid) * 64 + 32 * u.jh + 16 * jb + q) * HD + 8 * g; qf[jb][0] = __builtin_nontemporal_load((const bf16x8*)qp); qf[jb][1] = __builtin_nontemporal_load((const bf16x8*)(qp + 32)); }
;         ATT_WAIT_BAR();
.LBB0_263:
	s_cmp_eq_u32 s98, 2
	s_cbranch_scc1 .LBB0_336
	s_cmpk_gt_i32 s86, 0xff
	s_cbranch_scc1 .LBB0_336
	s_add_u32 s22, s28, 0x12000000
	s_addc_u32 s23, s29, 0
	s_add_u32 s40, s28, 0xe000000
	s_addc_u32 s41, s29, 0
	s_and_b32 s0, s33, 0xffffffc0
	v_add_u32_e32 v99, s0, v166
	s_mul_i32 s0, s85, 0xcd
	s_lshr_b32 s1, s0, 10
	s_mul_i32 s4, s1, -5
	v_ashrrev_i32_e32 v2, 3, v166
	s_add_i32 s4, s4, s85
	v_lshl_add_u32 v4, s4, 3, v2
	s_add_i32 s4, s0, 0x668
	s_lshr_b32 s4, s4, 10
	s_add_i32 s43, s85, 8
	s_mul_i32 s5, s4, -5
	s_add_i32 s5, s5, s43
	v_lshl_add_u32 v5, s5, 3, v2
	s_add_i32 s5, s0, 0xcd0
	s_lshr_b32 s5, s5, 10
	s_add_i32 s48, s85, 16
	s_mul_i32 s6, s5, -5
	s_add_i32 s6, s6, s48
	v_lshl_add_u32 v6, s6, 3, v2
	s_add_i32 s6, s0, 0x1338
	v_lshrrev_b32_e32 v1, 2, v4
	s_lshr_b32 s6, s6, 10
	v_bfe_u32 v0, v2, 1, 1
	v_and_b32_e32 v3, 7, v166
	v_and_b32_e32 v1, 6, v1
	s_add_i32 s50, s85, 24
	s_mul_i32 s7, s6, -5
	v_bitop3_b32 v1, v1, v3, v0 bitop3:0x36
	s_add_i32 s7, s7, s50
	v_lshlrev_b32_e32 v102, 4, v1
	v_lshrrev_b32_e32 v1, 2, v5
	v_lshl_add_u32 v7, s7, 3, v2
	s_add_i32 s7, s0, 0x19a0
	v_and_b32_e32 v1, 6, v1
	s_lshr_b32 s7, s7, 10
	v_bitop3_b32 v1, v1, v3, v0 bitop3:0x36
	s_add_i32 s54, s85, 32
	s_mul_i32 s8, s7, -5
	v_lshlrev_b32_e32 v106, 4, v1
	v_lshrrev_b32_e32 v1, 2, v6
	s_add_i32 s8, s8, s54
	v_and_b32_e32 v1, 6, v1
	v_lshl_add_u32 v8, s8, 3, v2
	s_add_i32 s8, s0, 0x2008
	v_bitop3_b32 v1, v1, v3, v0 bitop3:0x36
	s_lshr_b32 s8, s8, 10
	v_lshlrev_b32_e32 v110, 4, v1
	v_lshrrev_b32_e32 v1, 2, v7
	s_add_i32 s64, s85, 40
	s_mul_i32 s9, s8, -5
	v_and_b32_e32 v1, 6, v1
	s_add_i32 s9, s9, s64
	v_bitop3_b32 v1, v1, v3, v0 bitop3:0x36
	v_lshl_add_u32 v9, s9, 3, v2
	s_add_i32 s9, s0, 0x2670
	v_lshlrev_b32_e32 v114, 4, v1
	v_lshrrev_b32_e32 v1, 2, v8
	s_lshr_b32 s9, s9, 10
	v_and_b32_e32 v1, 6, v1
	s_add_i32 s66, s85, 48
	s_mul_i32 s10, s9, -5
	v_bitop3_b32 v1, v1, v3, v0 bitop3:0x36
	s_add_i32 s10, s10, s66
	v_lshlrev_b32_e32 v118, 4, v1
	v_lshrrev_b32_e32 v1, 2, v9
	v_lshl_add_u32 v10, s10, 3, v2
	s_add_i32 s10, s0, 0x2cd8
	v_and_b32_e32 v1, 6, v1
	s_lshr_b32 s10, s10, 10
	v_bitop3_b32 v1, v1, v3, v0 bitop3:0x36
	s_add_i32 s68, s85, 56
	s_mul_i32 s11, s10, -5
	v_lshlrev_b32_e32 v122, 4, v1
	v_lshrrev_b32_e32 v1, 2, v10
	s_add_i32 s11, s11, s68
	v_and_b32_e32 v1, 6, v1
	v_lshl_add_u32 v11, s11, 3, v2
	s_add_i32 s11, s0, 0x3340
	v_bitop3_b32 v1, v1, v3, v0 bitop3:0x36
	s_lshr_b32 s11, s11, 10
	v_lshlrev_b32_e32 v126, 4, v1
	v_lshrrev_b32_e32 v1, 2, v11
	s_add_i32 s70, s85, 64
	s_mul_i32 s12, s11, -5
	v_and_b32_e32 v1, 6, v1
	s_add_i32 s12, s12, s70
	s_addk_i32 s0, 0x39a8
	v_bitop3_b32 v1, v1, v3, v0 bitop3:0x36
	v_lshl_add_u32 v12, s12, 3, v2
	s_lshr_b32 s0, s0, 10
	v_lshlrev_b32_e32 v130, 4, v1
	v_lshrrev_b32_e32 v1, 2, v12
	s_add_i32 s72, s85, 0x48
	s_mul_i32 s12, s0, -5
	v_and_b32_e32 v1, 6, v1
	s_add_i32 s12, s12, s72
	v_bitop3_b32 v1, v1, v3, v0 bitop3:0x36
	v_lshl_add_u32 v13, s12, 3, v2
	v_lshlrev_b32_e32 v134, 4, v1
	v_lshrrev_b32_e32 v1, 2, v13
	v_and_b32_e32 v1, 6, v1
	v_bitop3_b32 v0, v1, v3, v0 bitop3:0x36
	v_lshlrev_b32_e32 v138, 4, v0
	v_lshlrev_b32_e32 v0, 3, v169
	v_ashrrev_i32_e32 v1, 31, v0
	v_lshl_add_u64 v[140:141], v[0:1], 1, s[36:37]
	v_and_b32_e32 v1, 2, v2
	v_lshrrev_b32_e32 v2, 1, v4
	v_and_b32_e32 v2, 4, v2
	v_bitop3_b32 v2, v2, v3, v1 bitop3:0x36
	v_lshlrev_b32_e32 v142, 4, v2
	v_lshrrev_b32_e32 v2, 1, v5
	v_and_b32_e32 v2, 4, v2
	v_bitop3_b32 v2, v2, v3, v1 bitop3:0x36
	v_lshlrev_b32_e32 v144, 4, v2
	v_lshrrev_b32_e32 v2, 1, v6
	v_and_b32_e32 v2, 4, v2
	v_bitop3_b32 v2, v2, v3, v1 bitop3:0x36
	v_lshlrev_b32_e32 v146, 4, v2
	v_lshrrev_b32_e32 v2, 1, v7
	v_and_b32_e32 v2, 4, v2
	v_bitop3_b32 v2, v2, v3, v1 bitop3:0x36
	v_lshlrev_b32_e32 v148, 4, v2
	v_lshrrev_b32_e32 v2, 1, v8
	v_and_b32_e32 v2, 4, v2
	v_bitop3_b32 v2, v2, v3, v1 bitop3:0x36
	v_lshlrev_b32_e32 v150, 4, v2
	v_lshrrev_b32_e32 v2, 1, v9
	v_and_b32_e32 v2, 4, v2
	v_bitop3_b32 v2, v2, v3, v1 bitop3:0x36
	v_lshlrev_b32_e32 v152, 4, v2
	v_lshrrev_b32_e32 v2, 1, v10
	v_and_b32_e32 v2, 4, v2
	v_bitop3_b32 v2, v2, v3, v1 bitop3:0x36
	v_lshlrev_b32_e32 v154, 4, v2
	v_lshrrev_b32_e32 v2, 1, v11
	v_and_b32_e32 v2, 4, v2
	v_bitop3_b32 v2, v2, v3, v1 bitop3:0x36
	v_lshlrev_b32_e32 v156, 4, v2
	v_lshrrev_b32_e32 v2, 1, v12
	v_and_b32_e32 v2, 4, v2
	v_bitop3_b32 v2, v2, v3, v1 bitop3:0x36
; __device__ __forceinline__ void p2_attention(Frame& F, const bf16_t* Qg, const bf16_t* Kg, const bf16_t* Vg, bf16_t* MIX) {
;     ...
;                 const int o = 8 * jb, kcol0 = 24 * u.jh + o, cq = 32 * u.jh + 16 * jb + q;
;                 int cs = cq - 8; cs = cs < 0 ? 0 : cs; cs = cs > 48 ? 48 : cs;
;                 f32x4 sc[8][2];
;                 {
;                     const int fk = ((q >> 1) & 1) | (((jb + (q >> 2)) & 3) << 1), x0 = g ^ fk;
;                     const LAS unsigned char* ka = lds + AT_A + (wbase * 40 + o + 8 * (q >> 2) + (q & 3)) * 128;
;                     const LAS unsigned char* k0p = ka + x0 * 16;
;                     const LAS unsigned char* k1p = ka + (x0 ^ 4) * 16;
; #pragma unroll
;                     for (int wl = 0; wl < 8; ++wl)
; #pragma unroll
;                         for (int blk = 0; blk < 2; ++blk) {
;                             const bf16x8 k0 = *(const LAS bf16x8*)(k0p + wl * 5120 + blk * 512), k1 = *(const LAS bf16x8*)(k1p + wl * 5120 + blk * 512);
;                             f32x4 a = (f32x4){0.f, 0.f, 0.f, 0.f};
;                             a = __builtin_amdgcn_mfma_f32_16x16x32_bf16(k0, qf[jb][0], a, 0, 0, 0);
;                             a = __builtin_amdgcn_mfma_f32_16x16x32_bf16(k1, qf[jb][1], a, 0, 0, 0);
;                             sc[wl][blk] = a;
;                         }
;                 }
;                 const LAS float* tab = (const LAS float*)(lds + AT_TAB) + (rs - r + 7) * 64 + 16 + (kcol0 - cq + 15) + 8 * g;
;                 const int voff = kcol0 + 8 * g - cs;
;                 float mx = -INFINITY;
; #pragma unroll
;                 for (int wl = 0; wl < 8; ++wl)
; #pragma unroll
;                     for (int blk = 0; blk < 2; ++blk)
; #pragma unroll
;                         for (int e = 0; e < 4; ++e) {
;                             const int ep = 4 * blk + e;
;                             float s_ = sc[wl][blk][e] + tab[wl * 64 + ep];
;                             s_ = ((unsigned)(voff + ep) < 16u) ? s_ : -INFINITY;
;                             sc[wl][blk][e] = s_; mx = fmaxf(mx, s_);
;                         }
;                 mx = fmaxf(mx, __shfl_xor(mx, 16)); mx = fmaxf(mx, __shfl_xor(mx, 32));
;     ...
;                     const int qr = q >> 2, p = lane & 3;
;                     const int fv = (((qr >> 1) & 1) << 1) | (((jb + g) & 1) << 2);
	v_lshlrev_b32_e32 v158, 4, v2
	v_lshrrev_b32_e32 v2, 1, v13
	v_and_b32_e32 v2, 4, v2
	v_bitop3_b32 v1, v2, v3, v1 bitop3:0x36
	s_lshl_b32 s4, s4, 13
	v_lshlrev_b32_e32 v160, 4, v1
	v_bfe_u32 v164, v166, 2, 2
	v_and_b32_e32 v1, 3, v166
	v_add_u32_e32 v170, 8, v0
	v_lshrrev_b32_e32 v0, 2, v166
	v_lshl_add_u32 v104, v5, 7, s4
	s_lshl_b32 s5, s5, 13
	s_add_i32 s12, 0, 0x12c00
	v_lshl_or_b32 v165, v164, 3, v1
	v_and_b32_e32 v5, 2, v0
	v_and_b32_e32 v0, 16, v96
	v_and_b32_e32 v1, 8, v96
	v_lshl_add_u32 v108, v6, 7, s5
	v_add3_u32 v6, s12, v0, v1
	v_lshlrev_b32_e32 v0, 6, v166
	v_mov_b32_e32 v97, 0
	v_and_b32_e32 v96, 0x3c0, v0
	v_and_b32_e32 v2, -16, v166
	s_lshl_b32 s1, s1, 13
	v_lshl_add_u64 v[0:1], s[24:25], 0, v[96:97]
	v_ashrrev_i32_e32 v3, 31, v2
	v_lshl_add_u32 v100, v4, 7, s1
	v_bfe_u32 v4, v166, 1, 1
	v_lshl_add_u64 v[162:163], v[0:1], 0, v[2:3]
	v_lshlrev_b32_e32 v0, 1, v164
	v_bitop3_b32 v1, v0, v169, v4 bitop3:0x36
	v_add_u32_e32 v0, 2, v0
	v_and_b32_e32 v0, 6, v0
	v_bitop3_b32 v0, v0, v169, v4 bitop3:0x36
	v_lshlrev_b32_e32 v173, 4, v0
	v_lshlrev_b32_e32 v0, 2, v169
	v_and_or_b32 v0, v0, 4, v5
	v_lshlrev_b32_e32 v176, 4, v0
	v_add_u32_e32 v0, 1, v169
	v_lshlrev_b32_e32 v171, 4, v1
	v_lshlrev_b32_e32 v1, 2, v0
	v_and_or_b32 v1, v1, 4, v5
	v_and_b32_e32 v185, 63, v166
	s_lshl_b32 s4, s43, 10
	s_lshl_b32 s5, s48, 10
	v_lshl_add_u32 v180, v0, 10, v6
	v_lshlrev_b32_e32 v181, 4, v1
	v_add_u32_e32 v0, -16, v185
	v_and_b32_e32 v1, 64, v168
	s_add_i32 s45, s4, 0
	s_add_i32 s49, s5, 0
	s_lshl_b32 s0, s0, 13
	s_add_i32 s37, s4, s12
	s_add_i32 s74, s5, s12
	v_cmp_gt_u32_e64 s[4:5], 31, v0
	v_xor_b32_e32 v0, 16, v168
	v_add_u32_e32 v1, 64, v1
	v_lshl_add_u32 v136, v13, 7, s0
	s_lshl_b32 s0, s72, 10
	v_cmp_lt_i32_e32 vcc, v0, v1
	s_lshl_b32 s1, s85, 10
	s_add_i32 s73, s0, 0
	s_add_i32 s81, s0, s12
	s_movk_i32 s0, 0x3c0
	v_cndmask_b32_e32 v0, v168, v0, vcc
	s_add_i32 s42, s1, 0
	s_add_i32 s36, s1, s12
	v_cmp_gt_i32_e64 s[20:21], s0, v99
	v_lshlrev_b32_e32 v186, 2, v0
	v_xor_b32_e32 v0, 32, v168
	s_add_i32 s0, 0, 0x25800
	s_lshl_b32 s1, s85, 8
	s_lshl_b32 s6, s6, 13
	s_lshl_b32 s7, s7, 13
	s_lshl_b32 s8, s8, 13
	s_lshl_b32 s9, s9, 13
	s_lshl_b32 s10, s10, 13
	s_lshl_b32 s11, s11, 13
	v_lshl_add_u32 v175, v169, 10, v6
	v_cmp_lt_i32_e32 vcc, v0, v1
	v_lshl_add_u32 v169, v169, 5, s0
	s_add_i32 s0, s0, s1
	v_and_b32_e32 v98, 15, v166
	v_lshl_add_u32 v112, v7, 7, s6
	s_lshl_b32 s6, s50, 10
	v_lshl_add_u32 v116, v8, 7, s7
	s_lshl_b32 s7, s54, 10
	v_lshl_add_u32 v120, v9, 7, s8
	s_lshl_b32 s8, s64, 10
	v_lshl_add_u32 v124, v10, 7, s9
	s_lshl_b32 s9, s66, 10
	v_lshl_add_u32 v128, v11, 7, s10
	s_lshl_b32 s10, s68, 10
	v_lshl_add_u32 v132, v12, 7, s11
	s_lshl_b32 s11, s70, 10
	v_cndmask_b32_e32 v0, v168, v0, vcc
	v_lshl_add_u32 v166, v166, 2, s0
	s_lshl_b32 s0, s86, 5
	v_ashrrev_i32_e32 v101, 31, v100
	v_mov_b32_e32 v103, v97
	v_ashrrev_i32_e32 v105, 31, v104
	v_mov_b32_e32 v107, v97
	v_ashrrev_i32_e32 v109, 31, v108
	v_mov_b32_e32 v111, v97
	v_ashrrev_i32_e32 v113, 31, v112
	v_mov_b32_e32 v115, v97
	s_add_i32 s51, s6, 0
	v_ashrrev_i32_e32 v117, 31, v116
	v_mov_b32_e32 v119, v97
	s_add_i32 s55, s7, 0
	v_ashrrev_i32_e32 v121, 31, v120
	v_mov_b32_e32 v123, v97
	s_add_i32 s65, s8, 0
	v_ashrrev_i32_e32 v125, 31, v124
	v_mov_b32_e32 v127, v97
	s_add_i32 s67, s9, 0
	v_ashrrev_i32_e32 v129, 31, v128
	v_mov_b32_e32 v131, v97
	s_add_i32 s69, s10, 0
	v_ashrrev_i32_e32 v133, 31, v132
	v_mov_b32_e32 v135, v97
	s_add_i32 s71, s11, 0
	v_ashrrev_i32_e32 v137, 31, v136
	v_mov_b32_e32 v139, v97
	v_mov_b32_e32 v143, v97
	v_mov_b32_e32 v145, v97
	v_mov_b32_e32 v147, v97
	v_mov_b32_e32 v149, v97
	s_add_i32 s75, s6, s12
	v_mov_b32_e32 v151, v97
	s_add_i32 s76, s7, s12
	v_mov_b32_e32 v153, v97
	s_add_i32 s77, s8, s12
	v_mov_b32_e32 v155, v97
	s_add_i32 s78, s9, s12
	v_mov_b32_e32 v157, v97
	s_add_i32 s79, s10, s12
	v_mov_b32_e32 v159, v97
	s_add_i32 s80, s11, s12
	v_mov_b32_e32 v161, v97
	v_xor_b32_e32 v172, 64, v171
	v_xor_b32_e32 v174, 64, v173
	v_xor_b32_e32 v177, 32, v176
	v_xor_b32_e32 v178, 64, v176
	v_xor_b32_e32 v179, 0x60, v176
	v_xor_b32_e32 v182, 32, v181
	v_xor_b32_e32 v183, 64, v181
	v_xor_b32_e32 v184, 0x60, v181
	s_lshl_b32 s82, s3, 3
	v_lshlrev_b32_e32 v168, 2, v0
	s_or_b32 s83, s0, 4
	s_lshl_b32 s86, s3, 5
	s_movk_i32 s87, 0x1bf
	s_mov_b32 s88, 0xff800000
	v_mov_b32_e32 v187, 0xff800000
	s_branch .LBB0_266

; __device__ __forceinline__ void p2_mixer(Frame& F) {
;     ...
;     for (int gw = F.vcu * NWAVES + F.wave; gw < M / 32; gw += F.G * NWAVES) pool_run(Zg, MIX, gw, F.lane);
;     p2_attention(F, Qg, Kg, Vg, MIX);
;     __syncthreads();
; }
.LBB0_336:
	s_cmp_lg_u32 s98, 1
	s_cbranch_scc1 .Lp2_end
	s_mov_b32 s98, 2
	s_mov_b32 s86, s99
	s_branch .Lp2_setup

; __host__ __device__ __forceinline__ size_t tl_off(int row, int k, int K) { return ((((size_t)(row >> 4) * (size_t)(K >> 5)) + (size_t)(k >> 5)) << 9) + (size_t)((row & 15) * 32 + (k & 31)); }
; #define ED_LOAD(i) do { const size_t o_ = (size_t)((((i) >> 2) * 8 + ((i) & 3)) * (D / 32)) * 512; xa[i][0] = __builtin_nontemporal_load((const u32x4*)(bp + o_)); xa[i][1] = __builtin_nontemporal_load((const u32x4*)(bp + o_ + 4 * 512)); } while (0)
;     __device__ __forceinline__ void operator()(const f32x4 (&acc)[2][2][4][2], const Unit& u, int wr, int wc, int fr, int fq) const {
;         const int row0 = u.pm * BM + wr * 64 + fr, col0 = u.pn * BM + wc * 32 + 8 * fq;
;         const bf16_t* __restrict__ bp = XB + tl_off(row0, col0, D);
;         const bool lodd = fr & 1; float* __restrict__ ope = out + (size_t)(row0 - (fr & 1)) * D + col0 + 4 * (fr & 1);
;         u32x4 xa[8][2];
;     ...
;         ED_LOAD(0); ED_LOAD(1); ED_LOAD(2); ED_LOAD(3);
;         asm volatile("" ::: "memory");
; #pragma unroll
;         for (int i = 0; i < 8; ++i) { const int ai = i >> 2, m = i & 3; const size_t o_ = (size_t)(ai * HALF + m * 16) * D;
; #pragma unroll
;             for (int bj = 0; bj < 2; ++bj) { const u32x4 w = xa[i][bj];
;                 const f32x4 r0 = {__builtin_bit_cast(float, w.x << 16), __builtin_bit_cast(float, w.x & 0xffff0000u), __builtin_bit_cast(float, w.y << 16), __builtin_bit_cast(float, w.y & 0xffff0000u)};
;                 const f32x4 r1 = {__builtin_bit_cast(float, w.z << 16), __builtin_bit_cast(float, w.z & 0xffff0000u), __builtin_bit_cast(float, w.w << 16), __builtin_bit_cast(float, w.w & 0xffff0000u)};
;                 const f32x4 vA = acc[ai][bj][m][0] + r0, vB = acc[ai][bj][m][1] + r1, t = lodd ? vA : vB; f32x4 g;
; #pragma unroll
;                 for (int e = 0; e < 4; ++e) { const float te = t[e]; g[e] = __builtin_bit_cast(float, __builtin_amdgcn_mov_dpp(__builtin_bit_cast(int, te), 0xB1, 0xf, 0xf, true)); }
;                 const f32x4 s1 = lodd ? g : vA, s2 = lodd ? vB : g;
;                 *(f32x4*)(ope + o_ + bj * HALF) = s1; *(f32x4*)(ope + D + o_ + bj * HALF) = s2; }
;             if (i + 4 < 8) { ED_LOAD((i + 4) & 7); }
.LBB0_574:
	s_lshl_b32 s4, s75, 8
	v_mov_b32_e32 v128, v159
	v_mov_b32_e32 v129, v158
	s_add_i32 s4, s4, s42
	s_nop 0
	v_add_u32_e32 v134, s4, v129
	s_lshl_b32 s4, s76, 8
	s_or_b32 s4, s4, s43
	v_lshlrev_b32_e32 v135, 3, v128
	v_add_u32_e32 v128, s4, v135
	v_ashrrev_i32_e32 v130, 4, v134
	v_ashrrev_i32_e32 v131, 31, v130
	v_ashrrev_i32_e32 v132, 5, v128
	v_lshlrev_b32_e32 v136, 5, v129
	v_ashrrev_i32_e32 v133, 31, v132
	v_and_b32_e32 v136, 0x1e0, v136
	v_lshlrev_b64 v[130:131], 15, v[130:131]
	v_and_or_b32 v135, v135, 24, v136
	v_lshl_add_u64 v[130:131], s[8:9], 0, v[130:131]
	v_lshlrev_b64 v[132:133], 10, v[132:133]
	v_lshl_add_u64 v[130:131], v[130:131], 0, v[132:133]
	v_lshlrev_b32_e32 v148, 1, v135
	v_lshl_add_u64 v[152:153], v[130:131], 0, v[148:149]
	global_load_dwordx4 v[166:169], v[152:153], off nt
	v_add_co_u32_e32 v130, vcc, s53, v152
	v_and_b32_e32 v165, 1, v129
	s_nop 0
	v_addc_co_u32_e32 v131, vcc, 0, v153, vcc
	global_load_dwordx4 v[170:173], v[130:131], off nt
	v_sub_u32_e32 v130, v134, v165
	v_ashrrev_i32_e32 v131, 31, v130
	v_lshlrev_b64 v[130:131], 12, v[130:131]
	v_ashrrev_i32_e32 v129, 31, v128
	v_lshl_add_u64 v[130:131], s[26:27], 0, v[130:131]
	v_lshl_add_u64 v[128:129], v[128:129], 2, v[130:131]
	v_lshlrev_b32_e32 v148, 4, v165
	v_lshl_add_u64 v[150:151], v[128:129], 0, v[148:149]
	v_add_co_u32_e32 v128, vcc, s54, v152
	s_nop 1
	v_addc_co_u32_e32 v129, vcc, 0, v153, vcc
	global_load_dwordx4 v[174:177], v[128:129], off offset:-4096 nt
	v_add_co_u32_e32 v130, vcc, s55, v152
	s_waitcnt vmcnt(2)
	v_lshlrev_b32_e32 v184, 16, v166
	v_addc_co_u32_e32 v131, vcc, 0, v153, vcc
	v_add_co_u32_e32 v182, vcc, s56, v152
	v_and_b32_e32 v185, 0xffff0000, v166
	s_nop 0
	v_addc_co_u32_e32 v183, vcc, 0, v153, vcc
	global_load_dwordx4 v[178:181], v[128:129], off nt
	global_load_dwordx4 v[140:143], v[130:131], off offset:-4096 nt
	global_load_dwordx4 v[136:139], v[130:131], off nt
	global_load_dwordx4 v[132:135], v[182:183], off offset:-4096 nt
	s_nop 0
	global_load_dwordx4 v[128:131], v[182:183], off nt
	v_add_co_u32_e32 v182, vcc, s53, v150
	v_lshlrev_b32_e32 v166, 16, v167
	s_nop 0
	v_addc_co_u32_e32 v183, vcc, 0, v151, vcc
	v_and_b32_e32 v167, 0xffff0000, v167
	v_lshlrev_b32_e32 v186, 16, v168
	v_and_b32_e32 v187, 0xffff0000, v168
	v_lshlrev_b32_e32 v168, 16, v169
	v_and_b32_e32 v169, 0xffff0000, v169
	v_pk_add_f32 v[124:125], v[124:125], v[184:185]
	v_pk_add_f32 v[126:127], v[126:127], v[166:167]
	v_pk_add_f32 v[166:167], v[120:121], v[186:187]
	v_pk_add_f32 v[168:169], v[122:123], v[168:169]
	v_cmp_eq_u32_e32 vcc, 0, v165
	s_waitcnt vmcnt(6)
	v_lshlrev_b32_e32 v184, 16, v170
	v_and_b32_e32 v185, 0xffff0000, v170
	v_cndmask_b32_e32 v120, v127, v169, vcc
	v_cndmask_b32_e32 v121, v126, v168, vcc
	v_cndmask_b32_e32 v122, v125, v167, vcc
	v_cndmask_b32_e32 v123, v124, v166, vcc
	v_mov_b32_dpp v186, v121 quad_perm:[1,0,3,2] row_mask:0xf bank_mask:0xf bound_ctrl:1
	v_mov_b32_dpp v165, v122 quad_perm:[1,0,3,2] row_mask:0xf bank_mask:0xf bound_ctrl:1
	v_mov_b32_dpp v148, v123 quad_perm:[1,0,3,2] row_mask:0xf bank_mask:0xf bound_ctrl:1
	v_mov_b32_dpp v187, v120 quad_perm:[1,0,3,2] row_mask:0xf bank_mask:0xf bound_ctrl:1
	v_cndmask_b32_e32 v123, v187, v127, vcc
	v_cndmask_b32_e32 v122, v186, v126, vcc
	v_cndmask_b32_e32 v121, v165, v125, vcc
	v_cndmask_b32_e32 v120, v148, v124, vcc
	v_lshlrev_b32_e32 v170, 16, v171
	v_cndmask_b32_e32 v127, v169, v187, vcc
	v_cndmask_b32_e32 v126, v168, v186, vcc
	v_cndmask_b32_e32 v125, v167, v165, vcc
	v_cndmask_b32_e32 v124, v166, v148, vcc
	global_store_dwordx4 v[150:151], v[120:123], off
	global_store_dwordx4 v[182:183], v[124:127], off
	v_and_b32_e32 v171, 0xffff0000, v171
	v_lshlrev_b32_e32 v120, 16, v172
	v_and_b32_e32 v121, 0xffff0000, v172
	v_lshlrev_b32_e32 v122, 16, v173
	v_and_b32_e32 v123, 0xffff0000, v173
	v_pk_add_f32 v[116:117], v[116:117], v[184:185]
	v_pk_add_f32 v[118:119], v[118:119], v[170:171]
	v_pk_add_f32 v[120:121], v[112:113], v[120:121]
	v_pk_add_f32 v[122:123], v[114:115], v[122:123]
	v_cndmask_b32_e32 v114, v117, v121, vcc
	v_cndmask_b32_e32 v112, v119, v123, vcc
	v_cndmask_b32_e32 v113, v118, v122, vcc
	v_cndmask_b32_e32 v115, v116, v120, vcc
	v_mov_b32_dpp v125, v114 quad_perm:[1,0,3,2] row_mask:0xf bank_mask:0xf bound_ctrl:1
	v_mov_b32_dpp v126, v113 quad_perm:[1,0,3,2] row_mask:0xf bank_mask:0xf bound_ctrl:1
	v_mov_b32_dpp v124, v115 quad_perm:[1,0,3,2] row_mask:0xf bank_mask:0xf bound_ctrl:1
	v_mov_b32_dpp v127, v112 quad_perm:[1,0,3,2] row_mask:0xf bank_mask:0xf bound_ctrl:1
	v_cndmask_b32_e32 v115, v127, v119, vcc
	v_cndmask_b32_e32 v114, v126, v118, vcc
	v_cndmask_b32_e32 v113, v125, v117, vcc
	v_cndmask_b32_e32 v112, v124, v116, vcc
	v_cndmask_b32_e32 v119, v123, v127, vcc
	v_cndmask_b32_e32 v118, v122, v126, vcc
	v_cndmask_b32_e32 v117, v121, v125, vcc
	v_cndmask_b32_e32 v116, v120, v124, vcc
	global_store_dwordx4 v[150:151], v[112:115], off offset:512
	global_store_dwordx4 v[182:183], v[116:119], off offset:512
	s_waitcnt vmcnt(9)
; #define ED_LOAD(i) do { const size_t o_ = (size_t)((((i) >> 2) * 8 + ((i) & 3)) * (D / 32)) * 512; xa[i][0] = __builtin_nontemporal_load((const u32x4*)(bp + o_)); xa[i][1] = __builtin_nontemporal_load((const u32x4*)(bp + o_ + 4 * 512)); } while (0)
;     __device__ __forceinline__ void operator()(const f32x4 (&acc)[2][2][4][2], const Unit& u, int wr, int wc, int fr, int fq) const {
;     ...
;         u32x4 xa[8][2];
;     ...
;         ED_LOAD(0); ED_LOAD(1); ED_LOAD(2); ED_LOAD(3);
;         asm volatile("" ::: "memory");
; #pragma unroll
;         for (int i = 0; i < 8; ++i) { const int ai = i >> 2, m = i & 3; const size_t o_ = (size_t)(ai * HALF + m * 16) * D;
; #pragma unroll
;             for (int bj = 0; bj < 2; ++bj) { const u32x4 w = xa[i][bj];
;                 const f32x4 r0 = {__builtin_bit_cast(float, w.x << 16), __builtin_bit_cast(float, w.x & 0xffff0000u), __builtin_bit_cast(float, w.y << 16), __builtin_bit_cast(float, w.y & 0xffff0000u)};
;                 const f32x4 r1 = {__builtin_bit_cast(float, w.z << 16), __builtin_bit_cast(float, w.z & 0xffff0000u), __builtin_bit_cast(float, w.w << 16), __builtin_bit_cast(float, w.w & 0xffff0000u)};
;                 const f32x4 vA = acc[ai][bj][m][0] + r0, vB = acc[ai][bj][m][1] + r1, t = lodd ? vA : vB; f32x4 g;
; #pragma unroll
;                 for (int e = 0; e < 4; ++e) { const float te = t[e]; g[e] = __builtin_bit_cast(float, __builtin_amdgcn_mov_dpp(__builtin_bit_cast(int, te), 0xB1, 0xf, 0xf, true)); }
;                 const f32x4 s1 = lodd ? g : vA, s2 = lodd ? vB : g;
;                 *(f32x4*)(ope + o_ + bj * HALF) = s1; *(f32x4*)(ope + D + o_ + bj * HALF) = s2; }
;             if (i + 4 < 8) { ED_LOAD((i + 4) & 7); }
;             asm volatile("" ::: "memory"); }
	v_lshlrev_b32_e32 v120, 16, v174
	v_add_co_u32_e64 v112, s[4:5], s57, v152
	v_and_b32_e32 v121, 0xffff0000, v174
	v_lshlrev_b32_e32 v124, 16, v176
	v_and_b32_e32 v125, 0xffff0000, v176
	v_addc_co_u32_e64 v113, s[4:5], 0, v153, s[4:5]
	v_lshlrev_b32_e32 v122, 16, v175
	v_and_b32_e32 v123, 0xffff0000, v175
	v_lshlrev_b32_e32 v126, 16, v177
	v_and_b32_e32 v127, 0xffff0000, v177
	v_pk_add_f32 v[108:109], v[108:109], v[120:121]
	v_pk_add_f32 v[120:121], v[104:105], v[124:125]
	global_load_dwordx4 v[116:119], v[112:113], off offset:-4096 nt
	s_nop 0
	global_load_dwordx4 v[112:115], v[112:113], off nt
	v_pk_add_f32 v[110:111], v[110:111], v[122:123]
	v_pk_add_f32 v[122:123], v[106:107], v[126:127]
	v_cndmask_b32_e32 v107, v108, v120, vcc
	v_cndmask_b32_e32 v104, v111, v123, vcc
	v_cndmask_b32_e32 v106, v109, v121, vcc
	v_mov_b32_dpp v124, v107 quad_perm:[1,0,3,2] row_mask:0xf bank_mask:0xf bound_ctrl:1
	v_cndmask_b32_e32 v105, v110, v122, vcc
	v_mov_b32_dpp v125, v106 quad_perm:[1,0,3,2] row_mask:0xf bank_mask:0xf bound_ctrl:1
	v_mov_b32_dpp v127, v104 quad_perm:[1,0,3,2] row_mask:0xf bank_mask:0xf bound_ctrl:1
	v_cndmask_b32_e32 v104, v124, v108, vcc
	v_cndmask_b32_e32 v108, v120, v124, vcc
	v_add_co_u32_e64 v120, s[4:5], s31, v150
	v_mov_b32_dpp v126, v105 quad_perm:[1,0,3,2] row_mask:0xf bank_mask:0xf bound_ctrl:1
	v_cndmask_b32_e32 v105, v125, v109, vcc
	v_cndmask_b32_e32 v109, v121, v125, vcc
	v_addc_co_u32_e64 v121, s[4:5], 0, v151, s[4:5]
	v_cndmask_b32_e32 v106, v126, v110, vcc
	v_cndmask_b32_e32 v110, v122, v126, vcc
	v_add_co_u32_e64 v122, s[4:5], s55, v150
	v_cndmask_b32_e32 v107, v127, v111, vcc
	v_cndmask_b32_e32 v111, v123, v127, vcc
	v_addc_co_u32_e64 v123, s[4:5], 0, v151, s[4:5]
	global_store_dwordx4 v[122:123], v[104:107], off offset:-4096
	global_store_dwordx4 v[122:123], v[108:111], off
	s_waitcnt vmcnt(12)
	v_lshlrev_b32_e32 v104, 16, v178
	v_and_b32_e32 v105, 0xffff0000, v178
	v_lshlrev_b32_e32 v106, 16, v179
	v_and_b32_e32 v107, 0xffff0000, v179
	v_lshlrev_b32_e32 v108, 16, v180
	v_and_b32_e32 v109, 0xffff0000, v180
	v_lshlrev_b32_e32 v110, 16, v181
	v_and_b32_e32 v111, 0xffff0000, v181
	v_pk_add_f32 v[100:101], v[100:101], v[104:105]
	v_pk_add_f32 v[102:103], v[102:103], v[106:107]
	v_pk_add_f32 v[104:105], v[96:97], v[108:109]
	v_pk_add_f32 v[106:107], v[98:99], v[110:111]
	v_cndmask_b32_e32 v98, v101, v105, vcc
	v_cndmask_b32_e32 v96, v103, v107, vcc
	v_cndmask_b32_e32 v97, v102, v106, vcc
	v_cndmask_b32_e32 v99, v100, v104, vcc
	v_mov_b32_dpp v109, v98 quad_perm:[1,0,3,2] row_mask:0xf bank_mask:0xf bound_ctrl:1
	v_mov_b32_dpp v110, v97 quad_perm:[1,0,3,2] row_mask:0xf bank_mask:0xf bound_ctrl:1
	v_mov_b32_dpp v108, v99 quad_perm:[1,0,3,2] row_mask:0xf bank_mask:0xf bound_ctrl:1
	v_mov_b32_dpp v111, v96 quad_perm:[1,0,3,2] row_mask:0xf bank_mask:0xf bound_ctrl:1
	v_cndmask_b32_e32 v99, v111, v103, vcc
	v_cndmask_b32_e32 v98, v110, v102, vcc
	v_cndmask_b32_e32 v97, v109, v101, vcc
	v_cndmask_b32_e32 v96, v108, v100, vcc
	v_cndmask_b32_e32 v103, v107, v111, vcc
	v_cndmask_b32_e32 v102, v106, v110, vcc
	v_cndmask_b32_e32 v101, v105, v109, vcc
	v_cndmask_b32_e32 v100, v104, v108, vcc
	global_store_dwordx4 v[120:121], v[96:99], off offset:512
	global_store_dwordx4 v[122:123], v[100:103], off offset:512
	s_waitcnt vmcnt(13)
	v_lshlrev_b32_e32 v104, 16, v140
	v_add_co_u32_e64 v96, s[4:5], s58, v152
	v_and_b32_e32 v105, 0xffff0000, v140
	v_lshlrev_b32_e32 v108, 16, v142
	v_and_b32_e32 v109, 0xffff0000, v142
	v_addc_co_u32_e64 v97, s[4:5], 0, v153, s[4:5]
	v_lshlrev_b32_e32 v106, 16, v141
	v_and_b32_e32 v107, 0xffff0000, v141
	v_lshlrev_b32_e32 v110, 16, v143
	v_and_b32_e32 v111, 0xffff0000, v143
	v_pk_add_f32 v[92:93], v[92:93], v[104:105]
	v_pk_add_f32 v[104:105], v[88:89], v[108:109]
	global_load_dwordx4 v[100:103], v[96:97], off offset:-4096 nt
	s_nop 0
	global_load_dwordx4 v[96:99], v[96:97], off nt
	v_pk_add_f32 v[94:95], v[94:95], v[106:107]
	v_pk_add_f32 v[106:107], v[90:91], v[110:111]
	v_cndmask_b32_e32 v91, v92, v104, vcc
	v_cndmask_b32_e32 v88, v95, v107, vcc
	v_cndmask_b32_e32 v90, v93, v105, vcc
	v_mov_b32_dpp v108, v91 quad_perm:[1,0,3,2] row_mask:0xf bank_mask:0xf bound_ctrl:1
	v_cndmask_b32_e32 v89, v94, v106, vcc
	v_mov_b32_dpp v109, v90 quad_perm:[1,0,3,2] row_mask:0xf bank_mask:0xf bound_ctrl:1
	v_mov_b32_dpp v111, v88 quad_perm:[1,0,3,2] row_mask:0xf bank_mask:0xf bound_ctrl:1
	v_cndmask_b32_e32 v88, v108, v92, vcc
	v_cndmask_b32_e32 v92, v104, v108, vcc
	v_add_co_u32_e64 v104, s[4:5], s59, v150
	v_mov_b32_dpp v110, v89 quad_perm:[1,0,3,2] row_mask:0xf bank_mask:0xf bound_ctrl:1
	v_cndmask_b32_e32 v89, v109, v93, vcc
	v_cndmask_b32_e32 v93, v105, v109, vcc
	v_addc_co_u32_e64 v105, s[4:5], 0, v151, s[4:5]
	v_cndmask_b32_e32 v90, v110, v94, vcc
	v_cndmask_b32_e32 v94, v106, v110, vcc
	v_add_co_u32_e64 v106, s[4:5], s60, v150
	v_cndmask_b32_e32 v91, v111, v95, vcc
	v_cndmask_b32_e32 v95, v107, v111, vcc
	v_addc_co_u32_e64 v107, s[4:5], 0, v151, s[4:5]
	global_store_dwordx4 v[106:107], v[88:91], off offset:-4096
	global_store_dwordx4 v[106:107], v[92:95], off
	s_waitcnt vmcnt(16)
; #define ED_LOAD(i) do { const size_t o_ = (size_t)((((i) >> 2) * 8 + ((i) & 3)) * (D / 32)) * 512; xa[i][0] = __builtin_nontemporal_load((const u32x4*)(bp + o_)); xa[i][1] = __builtin_nontemporal_load((const u32x4*)(bp + o_ + 4 * 512)); } while (0)
;     __device__ __forceinline__ void operator()(const f32x4 (&acc)[2][2][4][2], const Unit& u, int wr, int wc, int fr, int fq) const {
;     ...
;         u32x4 xa[8][2];
;     ...
;         ED_LOAD(0); ED_LOAD(1); ED_LOAD(2); ED_LOAD(3);
;         asm volatile("" ::: "memory");
; #pragma unroll
;         for (int i = 0; i < 8; ++i) { const int ai = i >> 2, m = i & 3; const size_t o_ = (size_t)(ai * HALF + m * 16) * D;
; #pragma unroll
;             for (int bj = 0; bj < 2; ++bj) { const u32x4 w = xa[i][bj];
;                 const f32x4 r0 = {__builtin_bit_cast(float, w.x << 16), __builtin_bit_cast(float, w.x & 0xffff0000u), __builtin_bit_cast(float, w.y << 16), __builtin_bit_cast(float, w.y & 0xffff0000u)};
;                 const f32x4 r1 = {__builtin_bit_cast(float, w.z << 16), __builtin_bit_cast(float, w.z & 0xffff0000u), __builtin_bit_cast(float, w.w << 16), __builtin_bit_cast(float, w.w & 0xffff0000u)};
;                 const f32x4 vA = acc[ai][bj][m][0] + r0, vB = acc[ai][bj][m][1] + r1, t = lodd ? vA : vB; f32x4 g;
; #pragma unroll
;                 for (int e = 0; e < 4; ++e) { const float te = t[e]; g[e] = __builtin_bit_cast(float, __builtin_amdgcn_mov_dpp(__builtin_bit_cast(int, te), 0xB1, 0xf, 0xf, true)); }
;                 const f32x4 s1 = lodd ? g : vA, s2 = lodd ? vB : g;
;                 *(f32x4*)(ope + o_ + bj * HALF) = s1; *(f32x4*)(ope + D + o_ + bj * HALF) = s2; }
;             if (i + 4 < 8) { ED_LOAD((i + 4) & 7); }
;             asm volatile("" ::: "memory"); }
	v_lshlrev_b32_e32 v88, 16, v136
	v_and_b32_e32 v89, 0xffff0000, v136
	v_lshlrev_b32_e32 v90, 16, v137
	v_and_b32_e32 v91, 0xffff0000, v137
	v_lshlrev_b32_e32 v92, 16, v138
	v_and_b32_e32 v93, 0xffff0000, v138
	v_lshlrev_b32_e32 v94, 16, v139
	v_and_b32_e32 v95, 0xffff0000, v139
	v_pk_add_f32 v[84:85], v[84:85], v[88:89]
	v_pk_add_f32 v[86:87], v[86:87], v[90:91]
	v_pk_add_f32 v[88:89], v[80:81], v[92:93]
	v_pk_add_f32 v[90:91], v[82:83], v[94:95]
	v_cndmask_b32_e32 v82, v85, v89, vcc
	v_cndmask_b32_e32 v80, v87, v91, vcc
	v_cndmask_b32_e32 v81, v86, v90, vcc
	v_cndmask_b32_e32 v83, v84, v88, vcc
	v_mov_b32_dpp v93, v82 quad_perm:[1,0,3,2] row_mask:0xf bank_mask:0xf bound_ctrl:1
	v_mov_b32_dpp v94, v81 quad_perm:[1,0,3,2] row_mask:0xf bank_mask:0xf bound_ctrl:1
	v_mov_b32_dpp v92, v83 quad_perm:[1,0,3,2] row_mask:0xf bank_mask:0xf bound_ctrl:1
	v_mov_b32_dpp v95, v80 quad_perm:[1,0,3,2] row_mask:0xf bank_mask:0xf bound_ctrl:1
	v_cndmask_b32_e32 v83, v95, v87, vcc
	v_cndmask_b32_e32 v82, v94, v86, vcc
	v_cndmask_b32_e32 v81, v93, v85, vcc
	v_cndmask_b32_e32 v80, v92, v84, vcc
	v_cndmask_b32_e32 v87, v91, v95, vcc
	v_cndmask_b32_e32 v86, v90, v94, vcc
	v_cndmask_b32_e32 v85, v89, v93, vcc
	v_cndmask_b32_e32 v84, v88, v92, vcc
	global_store_dwordx4 v[104:105], v[80:83], off offset:512
	global_store_dwordx4 v[106:107], v[84:87], off offset:512
	s_waitcnt vmcnt(17)
	v_lshlrev_b32_e32 v88, 16, v132
	v_add_co_u32_e64 v80, s[4:5], s61, v152
	v_and_b32_e32 v89, 0xffff0000, v132
	v_lshlrev_b32_e32 v92, 16, v134
	v_and_b32_e32 v93, 0xffff0000, v134
	v_addc_co_u32_e64 v81, s[4:5], 0, v153, s[4:5]
	v_lshlrev_b32_e32 v90, 16, v133
	v_and_b32_e32 v91, 0xffff0000, v133
	v_lshlrev_b32_e32 v94, 16, v135
	v_and_b32_e32 v95, 0xffff0000, v135
	v_pk_add_f32 v[76:77], v[76:77], v[88:89]
	v_pk_add_f32 v[88:89], v[72:73], v[92:93]
	global_load_dwordx4 v[84:87], v[80:81], off offset:-4096 nt
	s_nop 0
	global_load_dwordx4 v[80:83], v[80:81], off nt
	v_pk_add_f32 v[78:79], v[78:79], v[90:91]
	v_pk_add_f32 v[90:91], v[74:75], v[94:95]
	v_cndmask_b32_e32 v75, v76, v88, vcc
	v_cndmask_b32_e32 v72, v79, v91, vcc
	v_cndmask_b32_e32 v74, v77, v89, vcc
	v_mov_b32_dpp v92, v75 quad_perm:[1,0,3,2] row_mask:0xf bank_mask:0xf bound_ctrl:1
	v_cndmask_b32_e32 v73, v78, v90, vcc
	v_mov_b32_dpp v93, v74 quad_perm:[1,0,3,2] row_mask:0xf bank_mask:0xf bound_ctrl:1
	v_mov_b32_dpp v95, v72 quad_perm:[1,0,3,2] row_mask:0xf bank_mask:0xf bound_ctrl:1
	v_cndmask_b32_e32 v72, v92, v76, vcc
	v_cndmask_b32_e32 v76, v88, v92, vcc
	v_add_co_u32_e64 v88, s[4:5], s62, v150
	v_mov_b32_dpp v94, v73 quad_perm:[1,0,3,2] row_mask:0xf bank_mask:0xf bound_ctrl:1
	v_cndmask_b32_e32 v73, v93, v77, vcc
	v_cndmask_b32_e32 v77, v89, v93, vcc
	v_addc_co_u32_e64 v89, s[4:5], 0, v151, s[4:5]
	v_cndmask_b32_e32 v74, v94, v78, vcc
	v_cndmask_b32_e32 v78, v90, v94, vcc
	v_add_co_u32_e64 v90, s[4:5], s63, v150
	v_cndmask_b32_e32 v75, v95, v79, vcc
	v_cndmask_b32_e32 v79, v91, v95, vcc
	v_addc_co_u32_e64 v91, s[4:5], 0, v151, s[4:5]
	global_store_dwordx4 v[90:91], v[72:75], off offset:-4096
	global_store_dwordx4 v[90:91], v[76:79], off
	s_waitcnt vmcnt(20)
	v_lshlrev_b32_e32 v72, 16, v128
	v_and_b32_e32 v73, 0xffff0000, v128
	v_lshlrev_b32_e32 v74, 16, v129
	v_and_b32_e32 v75, 0xffff0000, v129
	v_lshlrev_b32_e32 v76, 16, v130
	v_and_b32_e32 v77, 0xffff0000, v130
	v_lshlrev_b32_e32 v78, 16, v131
	v_and_b32_e32 v79, 0xffff0000, v131
	v_pk_add_f32 v[68:69], v[68:69], v[72:73]
	v_pk_add_f32 v[70:71], v[70:71], v[74:75]
	v_pk_add_f32 v[72:73], v[64:65], v[76:77]
	v_pk_add_f32 v[74:75], v[66:67], v[78:79]
	v_cndmask_b32_e32 v66, v69, v73, vcc
	v_cndmask_b32_e32 v64, v71, v75, vcc
	v_cndmask_b32_e32 v65, v70, v74, vcc
	v_cndmask_b32_e32 v67, v68, v72, vcc
	v_mov_b32_dpp v77, v66 quad_perm:[1,0,3,2] row_mask:0xf bank_mask:0xf bound_ctrl:1
	v_mov_b32_dpp v78, v65 quad_perm:[1,0,3,2] row_mask:0xf bank_mask:0xf bound_ctrl:1
	v_mov_b32_dpp v76, v67 quad_perm:[1,0,3,2] row_mask:0xf bank_mask:0xf bound_ctrl:1
	v_mov_b32_dpp v79, v64 quad_perm:[1,0,3,2] row_mask:0xf bank_mask:0xf bound_ctrl:1
	v_cndmask_b32_e32 v67, v79, v71, vcc
	v_cndmask_b32_e32 v66, v78, v70, vcc
	v_cndmask_b32_e32 v65, v77, v69, vcc
	v_cndmask_b32_e32 v64, v76, v68, vcc
	v_cndmask_b32_e32 v71, v75, v79, vcc
	v_cndmask_b32_e32 v70, v74, v78, vcc
	v_cndmask_b32_e32 v69, v73, v77, vcc
	v_cndmask_b32_e32 v68, v72, v76, vcc
	global_store_dwordx4 v[88:89], v[64:67], off offset:512
	global_store_dwordx4 v[90:91], v[68:71], off offset:512
	s_waitcnt vmcnt(17)
	v_lshlrev_b32_e32 v72, 16, v116
	v_add_co_u32_e64 v64, s[4:5], s64, v152
	v_and_b32_e32 v73, 0xffff0000, v116
	s_nop 0
	v_addc_co_u32_e64 v65, s[4:5], 0, v153, s[4:5]
	global_load_dwordx4 v[68:71], v[64:65], off offset:-4096 nt
	s_nop 0
	global_load_dwordx4 v[64:67], v[64:65], off nt
	v_lshlrev_b32_e32 v76, 16, v118
	v_and_b32_e32 v77, 0xffff0000, v118
	v_lshlrev_b32_e32 v74, 16, v117
	v_and_b32_e32 v75, 0xffff0000, v117
	v_lshlrev_b32_e32 v78, 16, v119
	v_and_b32_e32 v79, 0xffff0000, v119
	v_pk_add_f32 v[60:61], v[60:61], v[72:73]
	v_pk_add_f32 v[72:73], v[56:57], v[76:77]
	v_pk_add_f32 v[62:63], v[62:63], v[74:75]
	v_pk_add_f32 v[74:75], v[58:59], v[78:79]
	v_cndmask_b32_e32 v59, v60, v72, vcc
	v_cndmask_b32_e32 v56, v63, v75, vcc
	v_cndmask_b32_e32 v58, v61, v73, vcc
	v_mov_b32_dpp v76, v59 quad_perm:[1,0,3,2] row_mask:0xf bank_mask:0xf bound_ctrl:1
	v_cndmask_b32_e32 v57, v62, v74, vcc
	v_mov_b32_dpp v77, v58 quad_perm:[1,0,3,2] row_mask:0xf bank_mask:0xf bound_ctrl:1
	v_mov_b32_dpp v79, v56 quad_perm:[1,0,3,2] row_mask:0xf bank_mask:0xf bound_ctrl:1
	v_cndmask_b32_e32 v56, v76, v60, vcc
	v_cndmask_b32_e32 v60, v72, v76, vcc
	v_add_co_u32_e64 v72, s[4:5], s65, v150
	v_mov_b32_dpp v78, v57 quad_perm:[1,0,3,2] row_mask:0xf bank_mask:0xf bound_ctrl:1
	v_cndmask_b32_e32 v57, v77, v61, vcc
	v_cndmask_b32_e32 v61, v73, v77, vcc
	v_addc_co_u32_e64 v73, s[4:5], 0, v151, s[4:5]
	v_cndmask_b32_e32 v58, v78, v62, vcc
	v_cndmask_b32_e32 v62, v74, v78, vcc
	v_add_co_u32_e64 v74, s[4:5], s66, v150
	v_cndmask_b32_e32 v59, v79, v63, vcc
	v_cndmask_b32_e32 v63, v75, v79, vcc
	v_addc_co_u32_e64 v75, s[4:5], 0, v151, s[4:5]
	global_store_dwordx4 v[74:75], v[56:59], off offset:-4096
	global_store_dwordx4 v[74:75], v[60:63], off
	s_waitcnt vmcnt(20)
; #define ED_LOAD(i) do { const size_t o_ = (size_t)((((i) >> 2) * 8 + ((i) & 3)) * (D / 32)) * 512; xa[i][0] = __builtin_nontemporal_load((const u32x4*)(bp + o_)); xa[i][1] = __builtin_nontemporal_load((const u32x4*)(bp + o_ + 4 * 512)); } while (0)
;     __device__ __forceinline__ void operator()(const f32x4 (&acc)[2][2][4][2], const Unit& u, int wr, int wc, int fr, int fq) const {
;     ...
;         u32x4 xa[8][2];
;     ...
;         ED_LOAD(0); ED_LOAD(1); ED_LOAD(2); ED_LOAD(3);
;         asm volatile("" ::: "memory");
; #pragma unroll
;         for (int i = 0; i < 8; ++i) { const int ai = i >> 2, m = i & 3; const size_t o_ = (size_t)(ai * HALF + m * 16) * D;
; #pragma unroll
;             for (int bj = 0; bj < 2; ++bj) { const u32x4 w = xa[i][bj];
;                 const f32x4 r0 = {__builtin_bit_cast(float, w.x << 16), __builtin_bit_cast(float, w.x & 0xffff0000u), __builtin_bit_cast(float, w.y << 16), __builtin_bit_cast(float, w.y & 0xffff0000u)};
;                 const f32x4 r1 = {__builtin_bit_cast(float, w.z << 16), __builtin_bit_cast(float, w.z & 0xffff0000u), __builtin_bit_cast(float, w.w << 16), __builtin_bit_cast(float, w.w & 0xffff0000u)};
;                 const f32x4 vA = acc[ai][bj][m][0] + r0, vB = acc[ai][bj][m][1] + r1, t = lodd ? vA : vB; f32x4 g;
; #pragma unroll
;                 for (int e = 0; e < 4; ++e) { const float te = t[e]; g[e] = __builtin_bit_cast(float, __builtin_amdgcn_mov_dpp(__builtin_bit_cast(int, te), 0xB1, 0xf, 0xf, true)); }
;                 const f32x4 s1 = lodd ? g : vA, s2 = lodd ? vB : g;
;                 *(f32x4*)(ope + o_ + bj * HALF) = s1; *(f32x4*)(ope + D + o_ + bj * HALF) = s2; }
;             if (i + 4 < 8) { ED_LOAD((i + 4) & 7); }
;             asm volatile("" ::: "memory"); }
	v_lshlrev_b32_e32 v56, 16, v112
	v_and_b32_e32 v57, 0xffff0000, v112
	v_lshlrev_b32_e32 v58, 16, v113
	v_and_b32_e32 v59, 0xffff0000, v113
	v_lshlrev_b32_e32 v60, 16, v114
	v_and_b32_e32 v61, 0xffff0000, v114
	v_lshlrev_b32_e32 v62, 16, v115
	v_and_b32_e32 v63, 0xffff0000, v115
	v_pk_add_f32 v[52:53], v[52:53], v[56:57]
	v_pk_add_f32 v[54:55], v[54:55], v[58:59]
	v_pk_add_f32 v[56:57], v[48:49], v[60:61]
	v_pk_add_f32 v[58:59], v[50:51], v[62:63]
	v_cndmask_b32_e32 v50, v53, v57, vcc
	v_cndmask_b32_e32 v48, v55, v59, vcc
	v_cndmask_b32_e32 v49, v54, v58, vcc
	v_cndmask_b32_e32 v51, v52, v56, vcc
	v_mov_b32_dpp v61, v50 quad_perm:[1,0,3,2] row_mask:0xf bank_mask:0xf bound_ctrl:1
	v_mov_b32_dpp v62, v49 quad_perm:[1,0,3,2] row_mask:0xf bank_mask:0xf bound_ctrl:1
	v_mov_b32_dpp v60, v51 quad_perm:[1,0,3,2] row_mask:0xf bank_mask:0xf bound_ctrl:1
	v_mov_b32_dpp v63, v48 quad_perm:[1,0,3,2] row_mask:0xf bank_mask:0xf bound_ctrl:1
	v_cndmask_b32_e32 v51, v63, v55, vcc
	v_cndmask_b32_e32 v50, v62, v54, vcc
	v_cndmask_b32_e32 v49, v61, v53, vcc
	v_cndmask_b32_e32 v48, v60, v52, vcc
	v_cndmask_b32_e32 v53, v57, v61, vcc
	v_cndmask_b32_e32 v52, v56, v60, vcc
	v_cndmask_b32_e32 v55, v59, v63, vcc
	v_cndmask_b32_e32 v54, v58, v62, vcc
	global_store_dwordx4 v[72:73], v[48:51], off offset:512
	global_store_dwordx4 v[74:75], v[52:55], off offset:512
	s_waitcnt vmcnt(17)
	v_lshlrev_b32_e32 v48, 16, v100
	v_and_b32_e32 v49, 0xffff0000, v100
	v_lshlrev_b32_e32 v52, 16, v102
	v_and_b32_e32 v53, 0xffff0000, v102
	v_lshlrev_b32_e32 v50, 16, v101
	v_and_b32_e32 v51, 0xffff0000, v101
	v_lshlrev_b32_e32 v54, 16, v103
	v_and_b32_e32 v55, 0xffff0000, v103
	v_pk_add_f32 v[44:45], v[44:45], v[48:49]
	v_pk_add_f32 v[48:49], v[40:41], v[52:53]
	v_pk_add_f32 v[46:47], v[46:47], v[50:51]
	v_pk_add_f32 v[50:51], v[42:43], v[54:55]
	v_cndmask_b32_e32 v43, v44, v48, vcc
	v_cndmask_b32_e32 v40, v47, v51, vcc
	v_cndmask_b32_e32 v42, v45, v49, vcc
	v_mov_b32_dpp v52, v43 quad_perm:[1,0,3,2] row_mask:0xf bank_mask:0xf bound_ctrl:1
	v_cndmask_b32_e32 v41, v46, v50, vcc
	v_mov_b32_dpp v53, v42 quad_perm:[1,0,3,2] row_mask:0xf bank_mask:0xf bound_ctrl:1
	v_mov_b32_dpp v55, v40 quad_perm:[1,0,3,2] row_mask:0xf bank_mask:0xf bound_ctrl:1
	v_cndmask_b32_e32 v40, v52, v44, vcc
	v_cndmask_b32_e32 v44, v48, v52, vcc
	v_add_co_u32_e64 v48, s[4:5], s67, v150
	v_mov_b32_dpp v54, v41 quad_perm:[1,0,3,2] row_mask:0xf bank_mask:0xf bound_ctrl:1
	v_cndmask_b32_e32 v41, v53, v45, vcc
	v_cndmask_b32_e32 v45, v49, v53, vcc
	v_addc_co_u32_e64 v49, s[4:5], 0, v151, s[4:5]
	v_cndmask_b32_e32 v42, v54, v46, vcc
	v_cndmask_b32_e32 v46, v50, v54, vcc
	v_add_co_u32_e64 v50, s[4:5], s68, v150
	v_cndmask_b32_e32 v43, v55, v47, vcc
	v_cndmask_b32_e32 v47, v51, v55, vcc
	v_addc_co_u32_e64 v51, s[4:5], 0, v151, s[4:5]
	global_store_dwordx4 v[50:51], v[40:43], off offset:-4096
	global_store_dwordx4 v[50:51], v[44:47], off
	s_waitcnt vmcnt(18)
	v_lshlrev_b32_e32 v40, 16, v96
	v_and_b32_e32 v41, 0xffff0000, v96
	v_lshlrev_b32_e32 v42, 16, v97
	v_and_b32_e32 v43, 0xffff0000, v97
	v_lshlrev_b32_e32 v44, 16, v98
	v_and_b32_e32 v45, 0xffff0000, v98
	v_lshlrev_b32_e32 v46, 16, v99
	v_and_b32_e32 v47, 0xffff0000, v99
	v_pk_add_f32 v[36:37], v[36:37], v[40:41]
	v_pk_add_f32 v[38:39], v[38:39], v[42:43]
	v_pk_add_f32 v[40:41], v[32:33], v[44:45]
	v_pk_add_f32 v[42:43], v[34:35], v[46:47]
	v_cndmask_b32_e32 v34, v37, v41, vcc
	v_cndmask_b32_e32 v32, v39, v43, vcc
	v_cndmask_b32_e32 v33, v38, v42, vcc
	v_cndmask_b32_e32 v35, v36, v40, vcc
	v_mov_b32_dpp v45, v34 quad_perm:[1,0,3,2] row_mask:0xf bank_mask:0xf bound_ctrl:1
	v_mov_b32_dpp v46, v33 quad_perm:[1,0,3,2] row_mask:0xf bank_mask:0xf bound_ctrl:1
	v_mov_b32_dpp v44, v35 quad_perm:[1,0,3,2] row_mask:0xf bank_mask:0xf bound_ctrl:1
	v_mov_b32_dpp v47, v32 quad_perm:[1,0,3,2] row_mask:0xf bank_mask:0xf bound_ctrl:1
	v_cndmask_b32_e32 v35, v47, v39, vcc
	v_cndmask_b32_e32 v34, v46, v38, vcc
	v_cndmask_b32_e32 v33, v45, v37, vcc
	v_cndmask_b32_e32 v32, v44, v36, vcc
	v_cndmask_b32_e32 v37, v41, v45, vcc
	v_cndmask_b32_e32 v36, v40, v44, vcc
	v_cndmask_b32_e32 v39, v43, v47, vcc
	v_cndmask_b32_e32 v38, v42, v46, vcc
	global_store_dwordx4 v[48:49], v[32:35], off offset:512
	global_store_dwordx4 v[50:51], v[36:39], off offset:512
	s_waitcnt vmcnt(15)
	v_lshlrev_b32_e32 v32, 16, v84
	v_and_b32_e32 v33, 0xffff0000, v84
	v_lshlrev_b32_e32 v36, 16, v86
	v_and_b32_e32 v37, 0xffff0000, v86
	v_lshlrev_b32_e32 v34, 16, v85
	v_and_b32_e32 v35, 0xffff0000, v85
	v_lshlrev_b32_e32 v38, 16, v87
	v_and_b32_e32 v39, 0xffff0000, v87
	v_pk_add_f32 v[28:29], v[28:29], v[32:33]
	v_pk_add_f32 v[32:33], v[24:25], v[36:37]
	v_pk_add_f32 v[30:31], v[30:31], v[34:35]
	v_pk_add_f32 v[34:35], v[26:27], v[38:39]
	v_cndmask_b32_e32 v27, v28, v32, vcc
	v_cndmask_b32_e32 v24, v31, v35, vcc
	v_cndmask_b32_e32 v26, v29, v33, vcc
	v_mov_b32_dpp v36, v27 quad_perm:[1,0,3,2] row_mask:0xf bank_mask:0xf bound_ctrl:1
	v_cndmask_b32_e32 v25, v30, v34, vcc
	v_mov_b32_dpp v37, v26 quad_perm:[1,0,3,2] row_mask:0xf bank_mask:0xf bound_ctrl:1
	v_mov_b32_dpp v39, v24 quad_perm:[1,0,3,2] row_mask:0xf bank_mask:0xf bound_ctrl:1
	v_cndmask_b32_e32 v24, v36, v28, vcc
	v_cndmask_b32_e32 v28, v32, v36, vcc
	v_add_co_u32_e64 v32, s[4:5], s69, v150
	v_mov_b32_dpp v38, v25 quad_perm:[1,0,3,2] row_mask:0xf bank_mask:0xf bound_ctrl:1
	v_cndmask_b32_e32 v25, v37, v29, vcc
	v_cndmask_b32_e32 v29, v33, v37, vcc
	v_addc_co_u32_e64 v33, s[4:5], 0, v151, s[4:5]
	v_cndmask_b32_e32 v26, v38, v30, vcc
	v_cndmask_b32_e32 v30, v34, v38, vcc
	v_add_co_u32_e64 v34, s[4:5], s70, v150
	v_cndmask_b32_e32 v27, v39, v31, vcc
	v_cndmask_b32_e32 v31, v35, v39, vcc
	v_addc_co_u32_e64 v35, s[4:5], 0, v151, s[4:5]
	global_store_dwordx4 v[34:35], v[24:27], off offset:-4096
	global_store_dwordx4 v[34:35], v[28:31], off
	s_waitcnt vmcnt(16)
; #define ED_LOAD(i) do { const size_t o_ = (size_t)((((i) >> 2) * 8 + ((i) & 3)) * (D / 32)) * 512; xa[i][0] = __builtin_nontemporal_load((const u32x4*)(bp + o_)); xa[i][1] = __builtin_nontemporal_load((const u32x4*)(bp + o_ + 4 * 512)); } while (0)
; #define PG8_BAR __builtin_amdgcn_s_barrier()
;     __device__ __forceinline__ void operator()(const f32x4 (&acc)[2][2][4][2], const Unit& u, int wr, int wc, int fr, int fq) const {
;     ...
;         u32x4 xa[8][2];
;     ...
;         ED_LOAD(0); ED_LOAD(1); ED_LOAD(2); ED_LOAD(3);
;         asm volatile("" ::: "memory");
; #pragma unroll
;         for (int i = 0; i < 8; ++i) { const int ai = i >> 2, m = i & 3; const size_t o_ = (size_t)(ai * HALF + m * 16) * D;
; #pragma unroll
;             for (int bj = 0; bj < 2; ++bj) { const u32x4 w = xa[i][bj];
;                 const f32x4 r0 = {__builtin_bit_cast(float, w.x << 16), __builtin_bit_cast(float, w.x & 0xffff0000u), __builtin_bit_cast(float, w.y << 16), __builtin_bit_cast(float, w.y & 0xffff0000u)};
;                 const f32x4 r1 = {__builtin_bit_cast(float, w.z << 16), __builtin_bit_cast(float, w.z & 0xffff0000u), __builtin_bit_cast(float, w.w << 16), __builtin_bit_cast(float, w.w & 0xffff0000u)};
;                 const f32x4 vA = acc[ai][bj][m][0] + r0, vB = acc[ai][bj][m][1] + r1, t = lodd ? vA : vB; f32x4 g;
; #pragma unroll
;                 for (int e = 0; e < 4; ++e) { const float te = t[e]; g[e] = __builtin_bit_cast(float, __builtin_amdgcn_mov_dpp(__builtin_bit_cast(int, te), 0xB1, 0xf, 0xf, true)); }
;                 const f32x4 s1 = lodd ? g : vA, s2 = lodd ? vB : g;
;                 *(f32x4*)(ope + o_ + bj * HALF) = s1; *(f32x4*)(ope + D + o_ + bj * HALF) = s2; }
;             if (i + 4 < 8) { ED_LOAD((i + 4) & 7); }
;             asm volatile("" ::: "memory"); }
;     ...
;         if constexpr (ALIGN_EPI) { if (wr == 0) PG8_BAR; }
;         if constexpr (!Epi::AFTER_DRAIN) { int fr_ = fr, fq_ = fq; asm volatile("" : "+v"(fr_), "+v"(fq_));
;             E(acc, cur, wr, wc, fr_, fq_); S.done(cur); }
;         if (!has_next) break;
;         cur = nxt; cA = nA; cB = nB; ++ui;
;         if constexpr (ALIGN_EPI) { if (wr == 1) PG8_BAR; }
;     }
	v_lshlrev_b32_e32 v24, 16, v80
	v_and_b32_e32 v25, 0xffff0000, v80
	v_lshlrev_b32_e32 v26, 16, v81
	v_and_b32_e32 v27, 0xffff0000, v81
	v_lshlrev_b32_e32 v28, 16, v82
	v_and_b32_e32 v29, 0xffff0000, v82
	v_lshlrev_b32_e32 v30, 16, v83
	v_and_b32_e32 v31, 0xffff0000, v83
	v_pk_add_f32 v[20:21], v[20:21], v[24:25]
	v_pk_add_f32 v[22:23], v[22:23], v[26:27]
	v_pk_add_f32 v[24:25], v[16:17], v[28:29]
	v_pk_add_f32 v[26:27], v[18:19], v[30:31]
	v_cndmask_b32_e32 v18, v21, v25, vcc
	v_cndmask_b32_e32 v16, v23, v27, vcc
	v_cndmask_b32_e32 v17, v22, v26, vcc
	v_cndmask_b32_e32 v19, v20, v24, vcc
	v_mov_b32_dpp v29, v18 quad_perm:[1,0,3,2] row_mask:0xf bank_mask:0xf bound_ctrl:1
	v_mov_b32_dpp v30, v17 quad_perm:[1,0,3,2] row_mask:0xf bank_mask:0xf bound_ctrl:1
	v_mov_b32_dpp v28, v19 quad_perm:[1,0,3,2] row_mask:0xf bank_mask:0xf bound_ctrl:1
	v_mov_b32_dpp v31, v16 quad_perm:[1,0,3,2] row_mask:0xf bank_mask:0xf bound_ctrl:1
	v_cndmask_b32_e32 v19, v31, v23, vcc
	v_cndmask_b32_e32 v18, v30, v22, vcc
	v_cndmask_b32_e32 v17, v29, v21, vcc
	v_cndmask_b32_e32 v16, v28, v20, vcc
	v_cndmask_b32_e32 v21, v25, v29, vcc
	v_cndmask_b32_e32 v20, v24, v28, vcc
	v_cndmask_b32_e32 v23, v27, v31, vcc
	v_cndmask_b32_e32 v22, v26, v30, vcc
	global_store_dwordx4 v[32:33], v[16:19], off offset:512
	global_store_dwordx4 v[34:35], v[20:23], off offset:512
	s_waitcnt vmcnt(13)
	v_lshlrev_b32_e32 v16, 16, v68
	v_and_b32_e32 v17, 0xffff0000, v68
	v_lshlrev_b32_e32 v20, 16, v70
	v_and_b32_e32 v21, 0xffff0000, v70
	v_lshlrev_b32_e32 v18, 16, v69
	v_and_b32_e32 v19, 0xffff0000, v69
	v_lshlrev_b32_e32 v22, 16, v71
	v_and_b32_e32 v23, 0xffff0000, v71
	v_pk_add_f32 v[12:13], v[12:13], v[16:17]
	v_pk_add_f32 v[16:17], v[8:9], v[20:21]
	v_pk_add_f32 v[14:15], v[14:15], v[18:19]
	v_pk_add_f32 v[18:19], v[10:11], v[22:23]
	v_cndmask_b32_e32 v11, v12, v16, vcc
	v_cndmask_b32_e32 v8, v15, v19, vcc
	v_cndmask_b32_e32 v10, v13, v17, vcc
	v_mov_b32_dpp v20, v11 quad_perm:[1,0,3,2] row_mask:0xf bank_mask:0xf bound_ctrl:1
	v_cndmask_b32_e32 v9, v14, v18, vcc
	v_mov_b32_dpp v21, v10 quad_perm:[1,0,3,2] row_mask:0xf bank_mask:0xf bound_ctrl:1
	v_mov_b32_dpp v23, v8 quad_perm:[1,0,3,2] row_mask:0xf bank_mask:0xf bound_ctrl:1
	v_cndmask_b32_e32 v8, v20, v12, vcc
	v_cndmask_b32_e32 v12, v16, v20, vcc
	v_add_co_u32_e64 v16, s[4:5], s71, v150
	v_mov_b32_dpp v22, v9 quad_perm:[1,0,3,2] row_mask:0xf bank_mask:0xf bound_ctrl:1
	v_cndmask_b32_e32 v9, v21, v13, vcc
	v_cndmask_b32_e32 v13, v17, v21, vcc
	v_addc_co_u32_e64 v17, s[4:5], 0, v151, s[4:5]
	v_cndmask_b32_e32 v10, v22, v14, vcc
	v_cndmask_b32_e32 v14, v18, v22, vcc
	v_add_co_u32_e64 v18, s[4:5], s72, v150
	v_cndmask_b32_e32 v11, v23, v15, vcc
	v_cndmask_b32_e32 v15, v19, v23, vcc
	v_addc_co_u32_e64 v19, s[4:5], 0, v151, s[4:5]
	global_store_dwordx4 v[18:19], v[8:11], off offset:-4096
	global_store_dwordx4 v[18:19], v[12:15], off
	s_waitcnt vmcnt(14)
	v_lshlrev_b32_e32 v8, 16, v64
	v_and_b32_e32 v9, 0xffff0000, v64
	v_lshlrev_b32_e32 v10, 16, v65
	v_and_b32_e32 v11, 0xffff0000, v65
	v_lshlrev_b32_e32 v12, 16, v66
	v_and_b32_e32 v13, 0xffff0000, v66
	v_lshlrev_b32_e32 v14, 16, v67
	v_and_b32_e32 v15, 0xffff0000, v67
	v_pk_add_f32 v[4:5], v[4:5], v[8:9]
	v_pk_add_f32 v[6:7], v[6:7], v[10:11]
	v_pk_add_f32 v[8:9], v[0:1], v[12:13]
	v_pk_add_f32 v[10:11], v[2:3], v[14:15]
	v_cndmask_b32_e32 v2, v5, v9, vcc
	v_cndmask_b32_e32 v0, v7, v11, vcc
	v_cndmask_b32_e32 v1, v6, v10, vcc
	v_cndmask_b32_e32 v3, v4, v8, vcc
	v_mov_b32_dpp v13, v2 quad_perm:[1,0,3,2] row_mask:0xf bank_mask:0xf bound_ctrl:1
	v_mov_b32_dpp v14, v1 quad_perm:[1,0,3,2] row_mask:0xf bank_mask:0xf bound_ctrl:1
	v_mov_b32_dpp v12, v3 quad_perm:[1,0,3,2] row_mask:0xf bank_mask:0xf bound_ctrl:1
	v_mov_b32_dpp v15, v0 quad_perm:[1,0,3,2] row_mask:0xf bank_mask:0xf bound_ctrl:1
	v_cndmask_b32_e32 v3, v15, v7, vcc
	v_cndmask_b32_e32 v2, v14, v6, vcc
	v_cndmask_b32_e32 v1, v13, v5, vcc
	v_cndmask_b32_e32 v0, v12, v4, vcc
	v_cndmask_b32_e32 v7, v11, v15, vcc
	v_cndmask_b32_e32 v6, v10, v14, vcc
	v_cndmask_b32_e32 v5, v9, v13, vcc
	v_cndmask_b32_e32 v4, v8, v12, vcc
	global_store_dwordx4 v[16:17], v[0:3], off offset:512
	global_store_dwordx4 v[18:19], v[4:7], off offset:512
	s_and_b64 vcc, exec, s[0:1]
	s_mov_b64 s[0:1], -1
	s_cbranch_vccnz .LBB0_559
	s_andn2_b64 vcc, exec, s[6:7]
	s_cbranch_vccnz .LBB0_558
	s_barrier
	s_branch .LBB0_558
